# added: x->f16 conversion loop unrolled x4 (8 loads in flight per lane)
# speedup vs baseline: 1.0038x; 1.0038x over previous
.LBB0_12:
	s_lshl_b32 s3, s2, 9
	v_mov_b32_e32 v1, v254
	v_writelane_b32 v255, s3, 3
	v_add_u32_e32 v2, s3, v1
	s_mov_b32 s3, 0x400000
	s_lshl_b32 s64, s38, 9
	v_cmp_gt_i32_e32 vcc, s3, v2
	s_and_saveexec_b64 s[4:5], vcc
	s_cbranch_execz .LBB0_15
	v_ashrrev_i32_e32 v3, 31, v2
	v_lshl_add_u64 v[4:5], v[2:3], 4, s[58:59]
	s_mov_b64 s[6:7], 0x4000000
	s_ashr_i32 s65, s64, 31
	v_lshlrev_b32_e32 v1, 1, v1
	v_lshl_add_u64 v[4:5], v[4:5], 0, s[6:7]
	s_lshl_b64 s[6:7], s[64:65], 4
	v_lshl_add_u32 v6, s2, 10, v1
	s_lshl_b32 s3, s38, 10
	s_mov_b64 s[8:9], 0
	s_mov_b32 s10, 0x3fffff
	s_lshl_b32 s16, s2, 9
	s_addk_i32 s16, 0x1ff
	s_mul_i32 s17, s64, 3
	s_add_i32 s16, s16, s17
	s_lshl_b32 s17, s64, 2
.Lx2u_loop:
	s_cmp_lt_i32 s16, 0x400000
	s_cbranch_scc0 .Lx2u_done
	v_ashrrev_i32_e32 v7, 31, v6
	v_lshl_add_u64 v[16:17], v[6:7], 4, s[40:41]
	global_load_dwordx4 v[8:11], v[16:17], off
	global_load_dwordx4 v[12:15], v[16:17], off offset:16
	v_add_u32_e32 v6, s3, v6
	v_ashrrev_i32_e32 v7, 31, v6
	v_lshl_add_u64 v[16:17], v[6:7], 4, s[40:41]
	global_load_dwordx4 v[32:35], v[16:17], off
	global_load_dwordx4 v[36:39], v[16:17], off offset:16
	v_add_u32_e32 v6, s3, v6
	v_ashrrev_i32_e32 v7, 31, v6
	v_lshl_add_u64 v[16:17], v[6:7], 4, s[40:41]
	global_load_dwordx4 v[40:43], v[16:17], off
	global_load_dwordx4 v[44:47], v[16:17], off offset:16
	v_add_u32_e32 v6, s3, v6
	v_ashrrev_i32_e32 v7, 31, v6
	v_lshl_add_u64 v[16:17], v[6:7], 4, s[40:41]
	global_load_dwordx4 v[48:51], v[16:17], off
	global_load_dwordx4 v[52:55], v[16:17], off offset:16
	v_add_u32_e32 v6, s3, v6
	s_waitcnt vmcnt(6)
	v_cvt_pk_f16_f32 v8, v8, v9
	v_cvt_pk_f16_f32 v9, v10, v11
	v_cvt_pk_f16_f32 v10, v12, v13
	v_cvt_pk_f16_f32 v11, v14, v15
	global_store_dwordx4 v[4:5], v[8:11], off
	v_lshl_add_u64 v[4:5], v[4:5], 0, s[6:7]
	s_waitcnt vmcnt(5)
	v_cvt_pk_f16_f32 v32, v32, v33
	v_cvt_pk_f16_f32 v33, v34, v35
	v_cvt_pk_f16_f32 v34, v36, v37
	v_cvt_pk_f16_f32 v35, v38, v39
	global_store_dwordx4 v[4:5], v[32:35], off
	v_lshl_add_u64 v[4:5], v[4:5], 0, s[6:7]
	s_waitcnt vmcnt(4)
	v_cvt_pk_f16_f32 v40, v40, v41
	v_cvt_pk_f16_f32 v41, v42, v43
	v_cvt_pk_f16_f32 v42, v44, v45
	v_cvt_pk_f16_f32 v43, v46, v47
	global_store_dwordx4 v[4:5], v[40:43], off
	v_lshl_add_u64 v[4:5], v[4:5], 0, s[6:7]
	s_waitcnt vmcnt(3)
	v_cvt_pk_f16_f32 v48, v48, v49
	v_cvt_pk_f16_f32 v49, v50, v51
	v_cvt_pk_f16_f32 v50, v52, v53
	v_cvt_pk_f16_f32 v51, v54, v55
	global_store_dwordx4 v[4:5], v[48:51], off
	v_lshl_add_u64 v[4:5], v[4:5], 0, s[6:7]
	v_add_u32_e32 v2, s17, v2
	s_add_i32 s16, s16, s17
	s_branch .Lx2u_loop
.Lx2u_done:
	v_cmp_gt_i32_e32 vcc, 0x400000, v2
	s_and_b64 exec, exec, vcc
	s_cbranch_execz .LBB0_15
